# att output: 16 short stores replaced by LDS transpose + one dwordx4 store per lane
# baseline (speedup 1.0000x reference)
.LBB0_1264:
	s_or_b64 exec, exec, s[8:9]
	v_lshrrev_b32_e32 v122, 3, v117
	v_lshl_add_u32 v119, v122, 2, s47
	s_waitcnt lgkmcnt(0)
	ds_read2_b32 v[4:5], v119 offset1:8
	ds_read2_b32 v[12:13], v119 offset0:16 offset1:24
	v_lshlrev_b32_e32 v6, 4, v120
	s_add_u32 s8, s20, s42
	v_and_b32_e32 v118, 0x70, v6
	s_waitcnt lgkmcnt(1)
	v_lshlrev_b32_e32 v4, 9, v4
	v_lshlrev_b32_e32 v5, 9, v5
	s_waitcnt lgkmcnt(0)
	v_lshlrev_b32_e32 v12, 9, v12
	v_lshlrev_b32_e32 v13, 9, v13
	s_addc_u32 s9, s21, 0
	v_and_or_b32 v4, v4, s43, v118
	v_and_or_b32 v8, v5, s43, v118
	v_and_or_b32 v12, v12, s43, v118
	v_and_or_b32 v16, v13, s43, v118
	global_load_dwordx4 v[4:7], v4, s[8:9]
	s_nop 0
	global_load_dwordx4 v[8:11], v8, s[8:9]
	ds_read2_b32 v[20:21], v119 offset0:32 offset1:40
	global_load_dwordx4 v[12:15], v12, s[8:9]
	s_nop 0
	global_load_dwordx4 v[16:19], v16, s[8:9]
	ds_read2_b32 v[28:29], v119 offset0:48 offset1:56
	s_add_u32 s18, s18, s42
	s_addc_u32 s19, s19, 0
	s_waitcnt lgkmcnt(1)
	v_lshlrev_b32_e32 v20, 9, v20
	v_lshlrev_b32_e32 v21, 9, v21
	s_waitcnt lgkmcnt(0)
	v_lshlrev_b32_e32 v28, 9, v28
	v_lshlrev_b32_e32 v29, 9, v29
	v_and_or_b32 v20, v20, s43, v118
	v_and_or_b32 v24, v21, s43, v118
	v_and_or_b32 v28, v28, s43, v118
	v_and_or_b32 v32, v29, s43, v118
	global_load_dwordx4 v[20:23], v20, s[8:9]
	s_nop 0
	global_load_dwordx4 v[24:27], v24, s[8:9]
	ds_read2_b32 v[36:37], v119 offset0:64 offset1:72
	global_load_dwordx4 v[28:31], v28, s[8:9]
	s_nop 0
	global_load_dwordx4 v[32:35], v32, s[8:9]
	ds_read2_b32 v[44:45], v119 offset0:80 offset1:88
	s_waitcnt lgkmcnt(1)
	v_lshlrev_b32_e32 v36, 9, v36
	v_lshlrev_b32_e32 v37, 9, v37
	s_waitcnt lgkmcnt(0)
	v_lshlrev_b32_e32 v44, 9, v44
	v_lshlrev_b32_e32 v45, 9, v45
	v_and_or_b32 v36, v36, s43, v118
	v_and_or_b32 v40, v37, s43, v118
	v_and_or_b32 v44, v44, s43, v118
	v_and_or_b32 v48, v45, s43, v118
	global_load_dwordx4 v[36:39], v36, s[8:9]
	s_nop 0
	global_load_dwordx4 v[40:43], v40, s[8:9]
	s_nop 0
	global_load_dwordx4 v[44:47], v44, s[8:9]
	s_nop 0
	global_load_dwordx4 v[48:51], v48, s[8:9]
	ds_read2_b32 v[52:53], v119 offset0:96 offset1:104
	ds_read2_b32 v[64:65], v119 offset0:112 offset1:120
	v_add_u32_e32 v112, s47, v112
	v_add_u32_e32 v121, s47, v118
	v_mad_u32_u24 v123, v116, s44, v112
	s_waitcnt lgkmcnt(1)
	v_lshlrev_b32_e32 v52, 9, v52
	v_lshlrev_b32_e32 v53, 9, v53
	s_waitcnt lgkmcnt(0)
	v_lshlrev_b32_e32 v64, 9, v64
	v_lshlrev_b32_e32 v65, 9, v65
	v_and_or_b32 v52, v52, s43, v118
	v_and_or_b32 v60, v53, s43, v118
	v_and_or_b32 v64, v64, s43, v118
	v_and_or_b32 v68, v65, s43, v118
	global_load_dwordx4 v[52:55], v52, s[8:9]
	s_nop 0
	global_load_dwordx4 v[60:63], v60, s[8:9]
	s_nop 0
	global_load_dwordx4 v[64:67], v64, s[8:9]
	s_nop 0
	global_load_dwordx4 v[68:71], v68, s[8:9]
	v_mad_u32_u24 v132, v122, s44, v121
	s_waitcnt vmcnt(15)
	ds_write_b128 v132, v[4:7] offset:1024
	s_waitcnt vmcnt(14)
	ds_write_b128 v132, v[8:11] offset:2304
	s_waitcnt vmcnt(13)
	ds_write_b128 v132, v[12:15] offset:3584
	s_waitcnt vmcnt(12)
	ds_write_b128 v132, v[16:19] offset:4864
	ds_read_b128 v[4:7], v123 offset:1024
	ds_read_b128 v[8:11], v123 offset:1088
	ds_read_b128 v[12:15], v123 offset:3584
	ds_read_b128 v[16:19], v123 offset:3648
	ds_read2_b32 v[72:73], v119 offset0:128 offset1:136
	ds_read2_b32 v[74:75], v119 offset0:144 offset1:152
	s_waitcnt lgkmcnt(5)
	v_mfma_f32_16x16x32_bf16 v[4:7], v[4:7], v[0:3], 0
	s_waitcnt lgkmcnt(1)
	v_lshlrev_b32_e32 v72, 9, v72
	v_mfma_f32_16x16x32_bf16 v[108:111], v[8:11], v[56:59], v[4:7]
	v_mfma_f32_16x16x32_bf16 v[12:15], v[12:15], v[0:3], 0
	s_nop 3
	v_and_or_b32 v4, v72, s43, v118
	v_lshlrev_b32_e32 v5, 9, v73
	s_waitcnt lgkmcnt(0)
	v_lshlrev_b32_e32 v72, 9, v74
	v_lshlrev_b32_e32 v73, 9, v75
	v_and_or_b32 v8, v5, s43, v118
	v_and_or_b32 v72, v72, s43, v118
	v_and_or_b32 v76, v73, s43, v118
	global_load_dwordx4 v[4:7], v4, s[8:9]
	s_nop 0
	global_load_dwordx4 v[8:11], v8, s[8:9]
	s_nop 0
	global_load_dwordx4 v[72:75], v72, s[8:9]
	s_nop 0
	global_load_dwordx4 v[76:79], v76, s[8:9]
	v_mfma_f32_16x16x32_bf16 v[104:107], v[16:19], v[56:59], v[12:15]
	s_waitcnt vmcnt(15)
	ds_write_b128 v132, v[20:23] offset:1024
	s_waitcnt vmcnt(14)
	ds_write_b128 v132, v[24:27] offset:2304
	s_waitcnt vmcnt(13)
	ds_write_b128 v132, v[28:31] offset:3584
	s_waitcnt vmcnt(12)
	ds_write_b128 v132, v[32:35] offset:4864
	ds_read_b128 v[12:15], v123 offset:1024
	ds_read_b128 v[16:19], v123 offset:1088
	ds_read_b128 v[20:23], v123 offset:3584
	ds_read_b128 v[24:27], v123 offset:3648
	ds_read2_b32 v[28:29], v119 offset0:160 offset1:168
	ds_read2_b32 v[30:31], v119 offset0:176 offset1:184
	s_waitcnt lgkmcnt(5)
	v_mfma_f32_16x16x32_bf16 v[12:15], v[12:15], v[0:3], 0
	s_waitcnt lgkmcnt(1)
	v_lshlrev_b32_e32 v28, 9, v28
	v_mfma_f32_16x16x32_bf16 v[100:103], v[16:19], v[56:59], v[12:15]
	v_mfma_f32_16x16x32_bf16 v[20:23], v[20:23], v[0:3], 0
	s_nop 3
	v_and_or_b32 v12, v28, s43, v118
	v_lshlrev_b32_e32 v13, 9, v29
	s_waitcnt lgkmcnt(0)
	v_lshlrev_b32_e32 v28, 9, v30
	v_lshlrev_b32_e32 v29, 9, v31
	v_and_or_b32 v16, v13, s43, v118
	v_and_or_b32 v28, v28, s43, v118
	v_and_or_b32 v32, v29, s43, v118
	global_load_dwordx4 v[12:15], v12, s[8:9]
	s_nop 0
	global_load_dwordx4 v[16:19], v16, s[8:9]
	s_nop 0
	global_load_dwordx4 v[28:31], v28, s[8:9]
	s_nop 0
	global_load_dwordx4 v[32:35], v32, s[8:9]
	v_mfma_f32_16x16x32_bf16 v[96:99], v[24:27], v[56:59], v[20:23]
	s_waitcnt vmcnt(15)
	ds_write_b128 v132, v[36:39] offset:1024
	s_waitcnt vmcnt(14)
	ds_write_b128 v132, v[40:43] offset:2304
	s_waitcnt vmcnt(13)
	ds_write_b128 v132, v[44:47] offset:3584
	s_waitcnt vmcnt(12)
	ds_write_b128 v132, v[48:51] offset:4864
	ds_read_b128 v[20:23], v123 offset:1024
	ds_read_b128 v[24:27], v123 offset:1088
	ds_read_b128 v[36:39], v123 offset:3584
	ds_read_b128 v[40:43], v123 offset:3648
	ds_read2_b32 v[44:45], v119 offset0:192 offset1:200
	ds_read2_b32 v[46:47], v119 offset0:208 offset1:216
	s_waitcnt lgkmcnt(5)
	v_mfma_f32_16x16x32_bf16 v[20:23], v[20:23], v[0:3], 0
	s_waitcnt lgkmcnt(1)
	v_lshlrev_b32_e32 v44, 9, v44
	v_mfma_f32_16x16x32_bf16 v[92:95], v[24:27], v[56:59], v[20:23]
	v_mfma_f32_16x16x32_bf16 v[36:39], v[36:39], v[0:3], 0
	s_nop 3
	v_and_or_b32 v20, v44, s43, v118
	v_lshlrev_b32_e32 v21, 9, v45
	s_waitcnt lgkmcnt(0)
	v_lshlrev_b32_e32 v44, 9, v46
	v_lshlrev_b32_e32 v45, 9, v47
	v_and_or_b32 v24, v21, s43, v118
	v_and_or_b32 v44, v44, s43, v118
	v_and_or_b32 v48, v45, s43, v118
	global_load_dwordx4 v[20:23], v20, s[8:9]
	s_nop 0
	global_load_dwordx4 v[24:27], v24, s[8:9]
	s_nop 0
	global_load_dwordx4 v[44:47], v44, s[8:9]
	s_nop 0
	global_load_dwordx4 v[48:51], v48, s[8:9]
	v_mfma_f32_16x16x32_bf16 v[88:91], v[40:43], v[56:59], v[36:39]
	s_waitcnt vmcnt(15)
	ds_write_b128 v132, v[52:55] offset:1024
	s_waitcnt vmcnt(14)
	ds_write_b128 v132, v[60:63] offset:2304
	s_waitcnt vmcnt(13)
	ds_write_b128 v132, v[64:67] offset:3584
	s_waitcnt vmcnt(12)
	ds_write_b128 v132, v[68:71] offset:4864
	ds_read_b128 v[36:39], v123 offset:1024
	ds_read_b128 v[40:43], v123 offset:1088
	ds_read_b128 v[52:55], v123 offset:3584
	ds_read_b128 v[60:63], v123 offset:3648
	ds_read2_b32 v[64:65], v119 offset0:224 offset1:232
	ds_read2_b32 v[66:67], v119 offset0:240 offset1:248
	s_waitcnt lgkmcnt(5)
	v_mfma_f32_16x16x32_bf16 v[36:39], v[36:39], v[0:3], 0
	s_waitcnt lgkmcnt(1)
	v_lshlrev_b32_e32 v64, 9, v64
	v_mfma_f32_16x16x32_bf16 v[84:87], v[40:43], v[56:59], v[36:39]
	v_mfma_f32_16x16x32_bf16 v[52:55], v[52:55], v[0:3], 0
	s_nop 3
	v_and_or_b32 v36, v64, s43, v118
	v_lshlrev_b32_e32 v37, 9, v65
	s_waitcnt lgkmcnt(0)
	v_lshlrev_b32_e32 v64, 9, v66
	v_and_or_b32 v40, v37, s43, v118
	v_and_or_b32 v64, v64, s43, v118
	v_lshlrev_b32_e32 v65, 9, v67
	global_load_dwordx4 v[36:39], v36, s[8:9]
	s_nop 0
	global_load_dwordx4 v[40:43], v40, s[8:9]
	v_and_or_b32 v65, v65, s43, v118
	global_load_dwordx4 v[124:127], v64, s[8:9]
	global_load_dwordx4 v[128:131], v65, s[8:9]
	v_mfma_f32_16x16x32_bf16 v[80:83], v[60:63], v[56:59], v[52:55]
	s_waitcnt vmcnt(15)
	ds_write_b128 v132, v[4:7] offset:1024
	s_waitcnt vmcnt(14)
	ds_write_b128 v132, v[8:11] offset:2304
	s_waitcnt vmcnt(13)
	ds_write_b128 v132, v[72:75] offset:3584
	s_waitcnt vmcnt(12)
	ds_write_b128 v132, v[76:79] offset:4864
	ds_read_b128 v[4:7], v123 offset:1024
	ds_read_b128 v[8:11], v123 offset:1088
	ds_read_b128 v[52:55], v123 offset:3584
	ds_read_b128 v[60:63], v123 offset:3648
	s_waitcnt lgkmcnt(3)
	v_mfma_f32_16x16x32_bf16 v[4:7], v[4:7], v[0:3], 0
	s_waitcnt lgkmcnt(1)
	v_mfma_f32_16x16x32_bf16 v[52:55], v[52:55], v[0:3], 0
	v_mfma_f32_16x16x32_bf16 v[76:79], v[8:11], v[56:59], v[4:7]
	s_waitcnt lgkmcnt(0)
	v_mfma_f32_16x16x32_bf16 v[72:75], v[60:63], v[56:59], v[52:55]
	s_waitcnt vmcnt(11)
	ds_write_b128 v132, v[12:15] offset:1024
	s_waitcnt vmcnt(10)
	ds_write_b128 v132, v[16:19] offset:2304
	s_waitcnt vmcnt(9)
	ds_write_b128 v132, v[28:31] offset:3584
	s_waitcnt vmcnt(8)
	ds_write_b128 v132, v[32:35] offset:4864
	ds_read_b128 v[4:7], v123 offset:1024
	ds_read_b128 v[8:11], v123 offset:1088
	ds_read_b128 v[12:15], v123 offset:3584
	ds_read_b128 v[16:19], v123 offset:3648
	s_waitcnt lgkmcnt(3)
	v_mfma_f32_16x16x32_bf16 v[4:7], v[4:7], v[0:3], 0
	s_waitcnt lgkmcnt(1)
	v_mfma_f32_16x16x32_bf16 v[12:15], v[12:15], v[0:3], 0
	v_mfma_f32_16x16x32_bf16 v[68:71], v[8:11], v[56:59], v[4:7]
	s_waitcnt lgkmcnt(0)
	v_mfma_f32_16x16x32_bf16 v[64:67], v[16:19], v[56:59], v[12:15]
	s_waitcnt vmcnt(7)
	ds_write_b128 v132, v[20:23] offset:1024
	s_waitcnt vmcnt(6)
	ds_write_b128 v132, v[24:27] offset:2304
	s_waitcnt vmcnt(5)
	ds_write_b128 v132, v[44:47] offset:3584
	s_waitcnt vmcnt(4)
	ds_write_b128 v132, v[48:51] offset:4864
	ds_read_b128 v[4:7], v123 offset:1024
	ds_read_b128 v[8:11], v123 offset:1088
	ds_read_b128 v[12:15], v123 offset:3584
	ds_read_b128 v[16:19], v123 offset:3648
	s_waitcnt lgkmcnt(3)
	v_mfma_f32_16x16x32_bf16 v[4:7], v[4:7], v[0:3], 0
	s_waitcnt lgkmcnt(1)
	v_mfma_f32_16x16x32_bf16 v[12:15], v[12:15], v[0:3], 0
	v_mfma_f32_16x16x32_bf16 v[60:63], v[8:11], v[56:59], v[4:7]
	s_waitcnt lgkmcnt(0)
	v_mfma_f32_16x16x32_bf16 v[52:55], v[16:19], v[56:59], v[12:15]
	s_waitcnt vmcnt(3)
	ds_write_b128 v132, v[36:39] offset:1024
	s_waitcnt vmcnt(2)
	ds_write_b128 v132, v[40:43] offset:2304
	s_waitcnt vmcnt(1)
	ds_write_b128 v132, v[124:127] offset:3584
	s_waitcnt vmcnt(0)
	ds_write_b128 v132, v[128:131] offset:4864
	ds_read_b128 v[4:7], v123 offset:1024
	ds_read_b128 v[8:11], v123 offset:1088
	ds_read_b128 v[12:15], v123 offset:3584
	ds_read_b128 v[124:127], v123 offset:3648
	s_waitcnt lgkmcnt(3)
	v_mfma_f32_16x16x32_bf16 v[4:7], v[4:7], v[0:3], 0
	s_waitcnt lgkmcnt(1)
	v_mfma_f32_16x16x32_bf16 v[128:131], v[12:15], v[0:3], 0
	ds_read2_b32 v[0:1], v119 offset1:8
	ds_read2_b32 v[2:3], v119 offset0:16 offset1:24
	s_waitcnt lgkmcnt(1)
	v_lshlrev_b32_e32 v0, 9, v0
	v_and_or_b32 v0, v0, s43, v118
	v_lshlrev_b32_e32 v1, 9, v1
	v_and_or_b32 v1, v1, s43, v118
	global_load_dwordx4 v[32:35], v0, s[18:19]
	global_load_dwordx4 v[36:39], v1, s[18:19]
	s_waitcnt lgkmcnt(0)
	v_lshlrev_b32_e32 v0, 9, v2
	v_and_or_b32 v2, v0, s43, v118
	ds_read2_b32 v[0:1], v119 offset0:32 offset1:40
	v_lshlrev_b32_e32 v3, 9, v3
	v_and_or_b32 v3, v3, s43, v118
	global_load_dwordx4 v[40:43], v2, s[18:19]
	global_load_dwordx4 v[44:47], v3, s[18:19]
	ds_read2_b32 v[2:3], v119 offset0:48 offset1:56
	s_waitcnt lgkmcnt(1)
	v_lshlrev_b32_e32 v0, 9, v0
	v_and_or_b32 v0, v0, s43, v118
	v_lshlrev_b32_e32 v1, 9, v1
	v_and_or_b32 v1, v1, s43, v118
	global_load_dwordx4 v[16:19], v0, s[18:19]
	global_load_dwordx4 v[20:23], v1, s[18:19]
	s_waitcnt lgkmcnt(0)
	v_lshlrev_b32_e32 v0, 9, v2
	v_and_or_b32 v2, v0, s43, v118
	v_lshlrev_b32_e32 v3, 9, v3
	v_mfma_f32_16x16x32_bf16 v[48:51], v[8:11], v[56:59], v[4:7]
	ds_read2_b32 v[0:1], v119 offset0:64 offset1:72
	v_and_or_b32 v3, v3, s43, v118
	global_load_dwordx4 v[24:27], v2, s[18:19]
	global_load_dwordx4 v[28:31], v3, s[18:19]
	ds_read2_b32 v[8:9], v119 offset0:80 offset1:88
	v_mfma_f32_16x16x32_bf16 v[56:59], v[124:127], v[56:59], v[128:131]
	s_waitcnt lgkmcnt(1)
	v_lshlrev_b32_e32 v0, 9, v0
	v_lshlrev_b32_e32 v1, 9, v1
	v_and_or_b32 v0, v0, s43, v118
	s_waitcnt lgkmcnt(0)
	v_lshlrev_b32_e32 v8, 9, v8
	v_lshlrev_b32_e32 v9, 9, v9
	v_and_or_b32 v4, v1, s43, v118
	v_and_or_b32 v8, v8, s43, v118
	v_and_or_b32 v12, v9, s43, v118
	global_load_dwordx4 v[0:3], v0, s[18:19]
	s_nop 0
	global_load_dwordx4 v[4:7], v4, s[18:19]
	s_nop 0
	global_load_dwordx4 v[8:11], v8, s[18:19]
	s_nop 0
	global_load_dwordx4 v[12:15], v12, s[18:19]
	v_and_b32_e32 v123, 12, v116
	v_add_u32_e32 v123, v112, v123
	v_and_b32_e32 v112, 3, v120
	v_lshl_add_u32 v112, v112, 2, s41
	ds_read_b32 v136, v123
	ds_read_b32 v137, v123 offset:64
	ds_read_b32 v138, v123 offset:128
	ds_read_b32 v139, v123 offset:192
	ds_read_b32 v140, v123 offset:256
	ds_read_b32 v141, v123 offset:320
	ds_read_b32 v142, v123 offset:384
	ds_read_b32 v143, v123 offset:448
	ds_read_b32 v144, v123 offset:512
	ds_read_b32 v145, v123 offset:576
	ds_read_b32 v146, v123 offset:640
	ds_read_b32 v147, v123 offset:704
	ds_read_b32 v148, v123 offset:768
	ds_read_b32 v149, v123 offset:832
	ds_read_b32 v150, v123 offset:896
	ds_read_b32 v151, v123 offset:960
	s_movk_i32 s8, 0x7c0
	v_mov_b32_e32 v168, 0xf149f2ca
	v_mov_b32_dpp v108, v109 row_shr:4 row_mask:0xf bank_mask:0x2
	v_mov_b32_dpp v104, v105 row_shr:4 row_mask:0xf bank_mask:0x2
	v_mov_b32_dpp v100, v101 row_shr:4 row_mask:0xf bank_mask:0x2
	v_mov_b32_dpp v96, v97 row_shr:4 row_mask:0xf bank_mask:0x2
	v_mov_b32_dpp v92, v93 row_shr:4 row_mask:0xf bank_mask:0x2
	v_mov_b32_dpp v88, v89 row_shr:4 row_mask:0xf bank_mask:0x2
	v_mov_b32_dpp v84, v85 row_shr:4 row_mask:0xf bank_mask:0x2
	v_mov_b32_dpp v80, v81 row_shr:4 row_mask:0xf bank_mask:0x2
	v_mov_b32_dpp v76, v77 row_shr:4 row_mask:0xf bank_mask:0x2
	v_mov_b32_dpp v72, v73 row_shr:4 row_mask:0xf bank_mask:0x2
	v_mov_b32_dpp v68, v69 row_shr:4 row_mask:0xf bank_mask:0x2
	v_mov_b32_dpp v64, v65 row_shr:4 row_mask:0xf bank_mask:0x2
	v_mov_b32_dpp v60, v61 row_shr:4 row_mask:0xf bank_mask:0x2
	v_mov_b32_dpp v52, v53 row_shr:4 row_mask:0xf bank_mask:0x2
	v_mov_b32_dpp v48, v49 row_shr:4 row_mask:0xf bank_mask:0x2
	v_mov_b32_dpp v56, v57 row_shr:4 row_mask:0xf bank_mask:0x2
	v_mov_b32_dpp v108, v110 row_shr:8 row_mask:0xf bank_mask:0x4
	v_mov_b32_dpp v104, v106 row_shr:8 row_mask:0xf bank_mask:0x4
	v_mov_b32_dpp v100, v102 row_shr:8 row_mask:0xf bank_mask:0x4
	v_mov_b32_dpp v96, v98 row_shr:8 row_mask:0xf bank_mask:0x4
	v_mov_b32_dpp v92, v94 row_shr:8 row_mask:0xf bank_mask:0x4
	v_mov_b32_dpp v88, v90 row_shr:8 row_mask:0xf bank_mask:0x4
	v_mov_b32_dpp v84, v86 row_shr:8 row_mask:0xf bank_mask:0x4
	v_mov_b32_dpp v80, v82 row_shr:8 row_mask:0xf bank_mask:0x4
	v_mov_b32_dpp v76, v78 row_shr:8 row_mask:0xf bank_mask:0x4
	v_mov_b32_dpp v72, v74 row_shr:8 row_mask:0xf bank_mask:0x4
	v_mov_b32_dpp v68, v70 row_shr:8 row_mask:0xf bank_mask:0x4
	v_mov_b32_dpp v64, v66 row_shr:8 row_mask:0xf bank_mask:0x4
	v_mov_b32_dpp v60, v62 row_shr:8 row_mask:0xf bank_mask:0x4
	v_mov_b32_dpp v52, v54 row_shr:8 row_mask:0xf bank_mask:0x4
	v_mov_b32_dpp v48, v50 row_shr:8 row_mask:0xf bank_mask:0x4
	v_mov_b32_dpp v56, v58 row_shr:8 row_mask:0xf bank_mask:0x4
	v_mov_b32_dpp v108, v111 row_shr:12 row_mask:0xf bank_mask:0x8
	v_mov_b32_dpp v104, v107 row_shr:12 row_mask:0xf bank_mask:0x8
	v_mov_b32_dpp v100, v103 row_shr:12 row_mask:0xf bank_mask:0x8
	v_mov_b32_dpp v96, v99 row_shr:12 row_mask:0xf bank_mask:0x8
	v_mov_b32_dpp v92, v95 row_shr:12 row_mask:0xf bank_mask:0x8
	v_mov_b32_dpp v88, v91 row_shr:12 row_mask:0xf bank_mask:0x8
	v_mov_b32_dpp v84, v87 row_shr:12 row_mask:0xf bank_mask:0x8
	v_mov_b32_dpp v80, v83 row_shr:12 row_mask:0xf bank_mask:0x8
	v_mov_b32_dpp v76, v79 row_shr:12 row_mask:0xf bank_mask:0x8
	v_mov_b32_dpp v72, v75 row_shr:12 row_mask:0xf bank_mask:0x8
	v_mov_b32_dpp v68, v71 row_shr:12 row_mask:0xf bank_mask:0x8
	v_mov_b32_dpp v64, v67 row_shr:12 row_mask:0xf bank_mask:0x8
	v_mov_b32_dpp v60, v63 row_shr:12 row_mask:0xf bank_mask:0x8
	v_mov_b32_dpp v52, v55 row_shr:12 row_mask:0xf bank_mask:0x8
	v_mov_b32_dpp v48, v51 row_shr:12 row_mask:0xf bank_mask:0x8
	v_mov_b32_dpp v56, v59 row_shr:12 row_mask:0xf bank_mask:0x8
	s_waitcnt lgkmcnt(15)
	v_lshrrev_b32_e32 v152, 10, v136
	v_and_or_b32 v152, v152, s8, v112
	s_waitcnt lgkmcnt(14)
	v_lshrrev_b32_e32 v153, 10, v137
	v_and_or_b32 v153, v153, s8, v112
	s_waitcnt lgkmcnt(13)
	v_lshrrev_b32_e32 v154, 10, v138
	v_and_or_b32 v154, v154, s8, v112
	s_waitcnt lgkmcnt(12)
	v_lshrrev_b32_e32 v155, 10, v139
	v_and_or_b32 v155, v155, s8, v112
	s_waitcnt lgkmcnt(11)
	v_lshrrev_b32_e32 v156, 10, v140
	v_and_or_b32 v156, v156, s8, v112
	s_waitcnt lgkmcnt(10)
	v_lshrrev_b32_e32 v157, 10, v141
	v_and_or_b32 v157, v157, s8, v112
	s_waitcnt lgkmcnt(9)
	v_lshrrev_b32_e32 v158, 10, v142
	v_and_or_b32 v158, v158, s8, v112
	s_waitcnt lgkmcnt(8)
	v_lshrrev_b32_e32 v159, 10, v143
	v_and_or_b32 v159, v159, s8, v112
	s_waitcnt lgkmcnt(7)
	v_lshrrev_b32_e32 v160, 10, v144
	v_and_or_b32 v160, v160, s8, v112
	s_waitcnt lgkmcnt(6)
	v_lshrrev_b32_e32 v161, 10, v145
	v_and_or_b32 v161, v161, s8, v112
	s_waitcnt lgkmcnt(5)
	v_lshrrev_b32_e32 v162, 10, v146
	v_and_or_b32 v162, v162, s8, v112
	s_waitcnt lgkmcnt(4)
	v_lshrrev_b32_e32 v163, 10, v147
	v_and_or_b32 v163, v163, s8, v112
	s_waitcnt lgkmcnt(3)
	v_lshrrev_b32_e32 v164, 10, v148
	v_and_or_b32 v164, v164, s8, v112
	s_waitcnt lgkmcnt(2)
	v_lshrrev_b32_e32 v165, 10, v149
	v_and_or_b32 v165, v165, s8, v112
	s_waitcnt lgkmcnt(1)
	v_lshrrev_b32_e32 v166, 10, v150
	v_and_or_b32 v166, v166, s8, v112
	s_waitcnt lgkmcnt(0)
	v_lshrrev_b32_e32 v167, 10, v151
	v_and_or_b32 v167, v167, s8, v112
	ds_read_b32 v152, v152
	ds_read_b32 v153, v153
	ds_read_b32 v154, v154
	ds_read_b32 v155, v155
	ds_read_b32 v156, v156
	ds_read_b32 v157, v157
	ds_read_b32 v158, v158
	ds_read_b32 v159, v159
	ds_read_b32 v160, v160
	ds_read_b32 v161, v161
	ds_read_b32 v162, v162
	ds_read_b32 v163, v163
	ds_read_b32 v164, v164
	ds_read_b32 v165, v165
	ds_read_b32 v166, v166
	ds_read_b32 v167, v167
	s_waitcnt lgkmcnt(15)
	v_fmac_f32_e32 v152, 0x3e000000, v108
	v_cmp_lt_u32_e64 s[20:21], s45, v136
	s_waitcnt lgkmcnt(14)
	v_fmac_f32_e32 v153, 0x3e000000, v104
	v_cmp_lt_u32_e64 s[8:9], s45, v137
	v_cndmask_b32_e64 v110, v168, v152, s[20:21]
	s_waitcnt lgkmcnt(13)
	v_fmac_f32_e32 v154, 0x3e000000, v100
	v_cmp_lt_u32_e64 s[20:21], s45, v138
	v_cndmask_b32_e64 v109, v168, v153, s[8:9]
	s_waitcnt lgkmcnt(12)
	v_fmac_f32_e32 v155, 0x3e000000, v96
	v_cmp_lt_u32_e64 s[8:9], s45, v139
	v_cndmask_b32_e64 v102, v168, v154, s[20:21]
	s_waitcnt lgkmcnt(11)
	v_fmac_f32_e32 v156, 0x3e000000, v92
	v_cmp_lt_u32_e64 s[20:21], s45, v140
	v_cndmask_b32_e64 v101, v168, v155, s[8:9]
	s_waitcnt lgkmcnt(10)
	v_fmac_f32_e32 v157, 0x3e000000, v88
	v_cmp_lt_u32_e64 s[8:9], s45, v141
	v_cndmask_b32_e64 v94, v168, v156, s[20:21]
	s_waitcnt lgkmcnt(9)
	v_fmac_f32_e32 v158, 0x3e000000, v84
	v_cmp_lt_u32_e64 s[20:21], s45, v142
	v_cndmask_b32_e64 v93, v168, v157, s[8:9]
	s_waitcnt lgkmcnt(8)
	v_fmac_f32_e32 v159, 0x3e000000, v80
	v_cmp_lt_u32_e64 s[8:9], s45, v143
	v_cndmask_b32_e64 v86, v168, v158, s[20:21]
	s_waitcnt lgkmcnt(7)
	v_fmac_f32_e32 v160, 0x3e000000, v76
	v_cmp_lt_u32_e64 s[20:21], s45, v144
	v_cndmask_b32_e64 v85, v168, v159, s[8:9]
	s_waitcnt lgkmcnt(6)
	v_fmac_f32_e32 v161, 0x3e000000, v72
	v_cmp_lt_u32_e64 s[8:9], s45, v145
	v_cndmask_b32_e64 v78, v168, v160, s[20:21]
	s_waitcnt lgkmcnt(5)
	v_fmac_f32_e32 v162, 0x3e000000, v68
	v_cmp_lt_u32_e64 s[20:21], s45, v146
	v_cndmask_b32_e64 v77, v168, v161, s[8:9]
	s_waitcnt lgkmcnt(4)
	v_fmac_f32_e32 v163, 0x3e000000, v64
	v_cmp_lt_u32_e64 s[8:9], s45, v147
	v_cndmask_b32_e64 v70, v168, v162, s[20:21]
	s_waitcnt lgkmcnt(3)
	v_fmac_f32_e32 v164, 0x3e000000, v60
	v_cmp_lt_u32_e64 s[20:21], s45, v148
	v_cndmask_b32_e64 v69, v168, v163, s[8:9]
	s_waitcnt lgkmcnt(2)
	v_fmac_f32_e32 v165, 0x3e000000, v52
	v_cmp_lt_u32_e64 s[8:9], s45, v149
	v_cndmask_b32_e64 v62, v168, v164, s[20:21]
	s_waitcnt lgkmcnt(1)
	v_fmac_f32_e32 v166, 0x3e000000, v48
	v_cmp_lt_u32_e64 s[20:21], s45, v150
	v_cndmask_b32_e64 v61, v168, v165, s[8:9]
	s_waitcnt lgkmcnt(0)
	v_fmac_f32_e32 v167, 0x3e000000, v56
	v_cmp_lt_u32_e64 s[8:9], s45, v151
	v_cndmask_b32_e64 v50, v168, v166, s[20:21]
	s_nop 1
	v_cndmask_b32_e64 v49, v168, v167, s[8:9]
	v_max3_f32 v48, v110, s46, v109
	v_max3_f32 v48, v48, v102, v101
	v_max3_f32 v48, v48, v94, v93
	v_max3_f32 v48, v48, v86, v85
	v_max3_f32 v48, v48, v78, v77
	v_max3_f32 v48, v48, v70, v69
	v_max3_f32 v48, v48, v62, v61
	v_max3_f32 v48, v48, v50, v49
	v_mov_b32_e32 v51, v113
	v_mov_b32_e32 v68, v113
	v_bfe_u32 v98, v120, 4, 2
	v_mov_b32_dpp v51, v48 row_ror:4 row_mask:0xf bank_mask:0xf
	v_max_f32_e32 v51, v51, v51
	v_max_f32_e32 v48, v48, v51
	v_mov_b32_e32 v51, v113
	v_lshrrev_b32_e32 v100, 2, v116
	v_lshl_or_b32 v98, v98, 2, v100
	v_mov_b32_dpp v51, v48 row_ror:8 row_mask:0xf bank_mask:0xf
	v_max_f32_e32 v51, v51, v51
	v_max_f32_e32 v48, v48, v51
	v_mov_b32_e32 v51, v48
	s_nop 1
	v_permlane16_swap_b32_e32 v48, v51
	v_max_f32_e32 v51, v51, v51
	v_max_f32_e32 v48, v48, v48
	v_max_f32_e32 v48, v48, v51
	v_mov_b32_e32 v51, v48
	s_nop 1
	v_permlane32_swap_b32_e32 v48, v51
	v_max_f32_e32 v51, v51, v51
	v_max_f32_e32 v48, v48, v48
	v_max_f32_e32 v48, v48, v51
	v_sub_f32_e32 v51, v110, v48
	v_mul_f32_e32 v51, 0x3fb8aa3b, v51
	v_sub_f32_e32 v52, v109, v48
	v_exp_f32_e32 v51, v51
	v_mul_f32_e32 v52, 0x3fb8aa3b, v52
	v_sub_f32_e32 v53, v102, v48
	v_exp_f32_e32 v52, v52
	v_mul_f32_e32 v53, 0x3fb8aa3b, v53
	v_sub_f32_e32 v54, v101, v48
	v_exp_f32_e32 v53, v53
	v_mul_f32_e32 v54, 0x3fb8aa3b, v54
	v_sub_f32_e32 v56, v94, v48
	v_exp_f32_e32 v54, v54
	v_mul_f32_e32 v56, 0x3fb8aa3b, v56
	v_sub_f32_e32 v57, v93, v48
	v_add_f32_e32 v55, 0, v51
	v_exp_f32_e32 v56, v56
	v_mul_f32_e32 v57, 0x3fb8aa3b, v57
	v_sub_f32_e32 v58, v86, v48
	v_add_f32_e32 v55, v52, v55
	v_exp_f32_e32 v57, v57
	v_mul_f32_e32 v58, 0x3fb8aa3b, v58
	v_sub_f32_e32 v59, v85, v48
	v_add_f32_e32 v55, v53, v55
	v_exp_f32_e32 v58, v58
	v_mul_f32_e32 v59, 0x3fb8aa3b, v59
	v_sub_f32_e32 v60, v78, v48
	v_add_f32_e32 v55, v54, v55
	v_exp_f32_e32 v59, v59
	v_mul_f32_e32 v60, 0x3fb8aa3b, v60
	v_sub_f32_e32 v63, v77, v48
	v_sub_f32_e32 v64, v70, v48
	v_add_f32_e32 v55, v56, v55
	v_exp_f32_e32 v60, v60
	v_mul_f32_e32 v63, 0x3fb8aa3b, v63
	v_mul_f32_e32 v64, 0x3fb8aa3b, v64
	v_add_f32_e32 v55, v57, v55
	v_exp_f32_e32 v63, v63
	v_exp_f32_e32 v101, v64
	v_sub_f32_e32 v64, v69, v48
	v_add_f32_e32 v55, v58, v55
	v_mul_f32_e32 v64, 0x3fb8aa3b, v64
	v_sub_f32_e32 v62, v62, v48
	v_add_f32_e32 v55, v59, v55
	v_exp_f32_e32 v102, v64
	v_mul_f32_e32 v62, 0x3fb8aa3b, v62
	v_sub_f32_e32 v61, v61, v48
	v_add_f32_e32 v55, v60, v55
	v_exp_f32_e32 v103, v62
	v_mul_f32_e32 v61, 0x3fb8aa3b, v61
	v_sub_f32_e32 v50, v50, v48
	v_add_f32_e32 v55, v63, v55
	v_exp_f32_e32 v104, v61
	v_mul_f32_e32 v50, 0x3fb8aa3b, v50
	v_sub_f32_e32 v48, v49, v48
	v_add_f32_e32 v55, v101, v55
	v_exp_f32_e32 v105, v50
	v_mul_f32_e32 v48, 0x3fb8aa3b, v48
	v_add_f32_e32 v55, v102, v55
	v_exp_f32_e32 v106, v48
	v_add_f32_e32 v48, v103, v55
	v_add_f32_e32 v48, v104, v48
	v_add_f32_e32 v48, v105, v48
	v_add_f32_e32 v48, v106, v48
	v_mov_b32_e32 v50, v113
	v_mov_b32_e32 v55, v113
	v_add_f32_dpp v48, v48, v48 row_ror:4 row_mask:0xf bank_mask:0xf bound_ctrl:1
	v_mov_b32_e32 v61, v113
	v_mov_b32_dpp v50, v51 row_shl:8 row_mask:0xf bank_mask:0x1 bound_ctrl:1
	v_add_f32_dpp v48, v48, v48 row_ror:8 row_mask:0xf bank_mask:0xf bound_ctrl:1
	v_mov_b32_e32 v49, v48
	s_nop 1
	v_permlane16_swap_b32_e32 v48, v49
	v_add_f32_e32 v96, v48, v49
	v_mov_b32_e32 v49, v113
	v_cndmask_b32_e32 v48, 0, v51, vcc
	v_mov_b32_dpp v55, v51 row_shl:12 row_mask:0xf bank_mask:0x1 bound_ctrl:1
	v_mov_b32_dpp v49, v51 row_shl:4 row_mask:0xf bank_mask:0x1 bound_ctrl:1
	v_cndmask_b32_e32 v51, 0, v52, vcc
	v_mov_b32_dpp v61, v52 row_shl:4 row_mask:0xf bank_mask:0x1 bound_ctrl:1
	v_mov_b32_e32 v62, v113
	v_mov_b32_e32 v64, v113
	v_cvt_pk_bf16_f32 v76, v48, v49
	v_cvt_pk_bf16_f32 v77, v50, v55
	v_cvt_pk_bf16_f32 v78, v51, v61
	v_mov_b32_e32 v49, v113
	v_mov_b32_e32 v50, v113
	v_mov_b32_e32 v51, v113
	v_mov_b32_dpp v62, v52 row_shl:8 row_mask:0xf bank_mask:0x1 bound_ctrl:1
	v_mov_b32_dpp v64, v52 row_shl:12 row_mask:0xf bank_mask:0x1 bound_ctrl:1
	v_cndmask_b32_e32 v48, 0, v53, vcc
	v_mov_b32_dpp v49, v53 row_shl:4 row_mask:0xf bank_mask:0x1 bound_ctrl:1
	v_mov_b32_dpp v50, v53 row_shl:8 row_mask:0xf bank_mask:0x1 bound_ctrl:1
	v_mov_b32_dpp v51, v53 row_shl:12 row_mask:0xf bank_mask:0x1 bound_ctrl:1
	v_cvt_pk_bf16_f32 v79, v62, v64
	v_mov_b32_e32 v53, v113
	v_cvt_pk_bf16_f32 v64, v48, v49
	v_cvt_pk_bf16_f32 v65, v50, v51
	v_mov_b32_e32 v49, v113
	v_mov_b32_e32 v50, v113
	v_mov_b32_e32 v51, v113
	v_cndmask_b32_e32 v52, 0, v54, vcc
	v_mov_b32_dpp v53, v54 row_shl:4 row_mask:0xf bank_mask:0x1 bound_ctrl:1
	v_cndmask_b32_e32 v48, 0, v56, vcc
	v_mov_b32_dpp v49, v56 row_shl:4 row_mask:0xf bank_mask:0x1 bound_ctrl:1
	v_mov_b32_dpp v50, v56 row_shl:8 row_mask:0xf bank_mask:0x1 bound_ctrl:1
	v_mov_b32_dpp v51, v56 row_shl:12 row_mask:0xf bank_mask:0x1 bound_ctrl:1
	v_cvt_pk_bf16_f32 v66, v52, v53
	v_cvt_pk_bf16_f32 v52, v48, v49
	v_cvt_pk_bf16_f32 v53, v50, v51
	v_mov_b32_e32 v51, v113
	ds_read2_b32 v[48:49], v119 offset0:96 offset1:104
	v_cndmask_b32_e32 v50, 0, v58, vcc
	v_mov_b32_dpp v51, v58 row_shl:4 row_mask:0xf bank_mask:0x1 bound_ctrl:1
	v_cvt_pk_bf16_f32 v72, v50, v51
	ds_read2_b32 v[50:51], v119 offset0:112 offset1:120
	s_waitcnt lgkmcnt(1)
	v_lshlrev_b32_e32 v48, 9, v48
	v_and_or_b32 v48, v48, s43, v118
	v_lshlrev_b32_e32 v49, 9, v49
	v_and_or_b32 v49, v49, s43, v118
	global_load_dwordx4 v[80:83], v48, s[18:19]
	global_load_dwordx4 v[84:87], v49, s[18:19]
	s_waitcnt lgkmcnt(0)
	v_lshlrev_b32_e32 v48, 9, v50
	v_and_or_b32 v48, v48, s43, v118
	v_lshlrev_b32_e32 v49, 9, v51
	v_and_or_b32 v49, v49, s43, v118
	global_load_dwordx4 v[88:91], v48, s[18:19]
	global_load_dwordx4 v[92:95], v49, s[18:19]
	v_mov_b32_e32 v55, v113
	v_mov_b32_e32 v61, v113
	v_mov_b32_e32 v56, v113
	v_mov_b32_dpp v55, v54 row_shl:8 row_mask:0xf bank_mask:0x1 bound_ctrl:1
	v_mov_b32_dpp v61, v54 row_shl:12 row_mask:0xf bank_mask:0x1 bound_ctrl:1
	v_cvt_pk_bf16_f32 v67, v55, v61
	v_mov_b32_e32 v55, v113
	v_mov_b32_e32 v61, v113
	v_cndmask_b32_e32 v54, 0, v57, vcc
	v_mov_b32_dpp v55, v57 row_shl:4 row_mask:0xf bank_mask:0x1 bound_ctrl:1
	v_mov_b32_dpp v56, v57 row_shl:8 row_mask:0xf bank_mask:0x1 bound_ctrl:1
	v_mov_b32_dpp v61, v57 row_shl:12 row_mask:0xf bank_mask:0x1 bound_ctrl:1
	v_cvt_pk_bf16_f32 v54, v54, v55
	v_cvt_pk_bf16_f32 v55, v56, v61
	v_mov_b32_e32 v56, v113
	v_mov_b32_e32 v57, v113
	v_mov_b32_e32 v61, v113
	v_mov_b32_dpp v56, v58 row_shl:8 row_mask:0xf bank_mask:0x1 bound_ctrl:1
	v_mov_b32_dpp v57, v58 row_shl:12 row_mask:0xf bank_mask:0x1 bound_ctrl:1
	v_cndmask_b32_e32 v58, 0, v59, vcc
	v_mov_b32_dpp v61, v59 row_shl:4 row_mask:0xf bank_mask:0x1 bound_ctrl:1
	v_mov_b32_e32 v62, v113
	v_mov_b32_dpp v68, v59 row_shl:12 row_mask:0xf bank_mask:0x1 bound_ctrl:1
	v_cvt_pk_bf16_f32 v74, v58, v61
	v_mov_b32_dpp v62, v59 row_shl:8 row_mask:0xf bank_mask:0x1 bound_ctrl:1
	v_mov_b32_e32 v49, v113
	v_mov_b32_e32 v50, v113
	v_mov_b32_e32 v51, v113
	v_mov_b32_e32 v58, v113
	v_mov_b32_e32 v59, v113
	v_cvt_pk_bf16_f32 v73, v56, v57
	v_cndmask_b32_e32 v48, 0, v60, vcc
	v_mov_b32_dpp v49, v60 row_shl:4 row_mask:0xf bank_mask:0x1 bound_ctrl:1
	v_mov_b32_dpp v50, v60 row_shl:8 row_mask:0xf bank_mask:0x1 bound_ctrl:1
	v_mov_b32_dpp v51, v60 row_shl:12 row_mask:0xf bank_mask:0x1 bound_ctrl:1
	v_mov_b32_e32 v57, v113
	v_mov_b32_dpp v58, v63 row_shl:8 row_mask:0xf bank_mask:0x1 bound_ctrl:1
	v_mov_b32_dpp v59, v63 row_shl:12 row_mask:0xf bank_mask:0x1 bound_ctrl:1
	v_cvt_pk_bf16_f32 v75, v62, v68
	v_cndmask_b32_e32 v56, 0, v63, vcc
	v_mov_b32_dpp v57, v63 row_shl:4 row_mask:0xf bank_mask:0x1 bound_ctrl:1
	v_cvt_pk_bf16_f32 v68, v48, v49
	v_cvt_pk_bf16_f32 v69, v50, v51
	v_cvt_pk_bf16_f32 v71, v58, v59
	v_mov_b32_e32 v49, v113
	v_mov_b32_e32 v50, v113
	v_mov_b32_e32 v51, v113
	v_mov_b32_e32 v58, v113
	v_mov_b32_e32 v59, v113
	v_cvt_pk_bf16_f32 v70, v56, v57
	v_cndmask_b32_e32 v48, 0, v101, vcc
	v_mov_b32_dpp v49, v101 row_shl:4 row_mask:0xf bank_mask:0x1 bound_ctrl:1
	v_mov_b32_dpp v50, v101 row_shl:8 row_mask:0xf bank_mask:0x1 bound_ctrl:1
	v_mov_b32_dpp v51, v101 row_shl:12 row_mask:0xf bank_mask:0x1 bound_ctrl:1
	v_mov_b32_e32 v57, v113
	v_mov_b32_dpp v58, v102 row_shl:8 row_mask:0xf bank_mask:0x1 bound_ctrl:1
	v_mov_b32_dpp v59, v102 row_shl:12 row_mask:0xf bank_mask:0x1 bound_ctrl:1
	v_cndmask_b32_e32 v56, 0, v102, vcc
	v_mov_b32_dpp v57, v102 row_shl:4 row_mask:0xf bank_mask:0x1 bound_ctrl:1
	v_cvt_pk_bf16_f32 v60, v48, v49
	v_cvt_pk_bf16_f32 v61, v50, v51
	v_cvt_pk_bf16_f32 v63, v58, v59
	v_mov_b32_e32 v49, v113
	v_mov_b32_e32 v50, v113
	v_mov_b32_e32 v51, v113
	v_mov_b32_e32 v59, v113
	v_mov_b32_e32 v101, v113
	v_mov_b32_e32 v102, v113
	v_cndmask_b32_e32 v48, 0, v103, vcc
	v_mov_b32_dpp v49, v103 row_shl:4 row_mask:0xf bank_mask:0x1 bound_ctrl:1
	v_mov_b32_dpp v50, v103 row_shl:8 row_mask:0xf bank_mask:0x1 bound_ctrl:1
	v_mov_b32_dpp v51, v103 row_shl:12 row_mask:0xf bank_mask:0x1 bound_ctrl:1
	v_cndmask_b32_e32 v58, 0, v104, vcc
	v_mov_b32_dpp v59, v104 row_shl:4 row_mask:0xf bank_mask:0x1 bound_ctrl:1
	v_mov_b32_dpp v101, v104 row_shl:8 row_mask:0xf bank_mask:0x1 bound_ctrl:1
	v_mov_b32_dpp v102, v104 row_shl:12 row_mask:0xf bank_mask:0x1 bound_ctrl:1
	v_cvt_pk_bf16_f32 v62, v56, v57
	v_cvt_pk_bf16_f32 v56, v48, v49
	v_cvt_pk_bf16_f32 v57, v50, v51
	v_cvt_pk_bf16_f32 v58, v58, v59
	v_cvt_pk_bf16_f32 v59, v101, v102
	v_mov_b32_e32 v49, v113
	v_mov_b32_e32 v50, v113
	v_mov_b32_e32 v51, v113
	v_mov_b32_e32 v102, v113
	v_mov_b32_e32 v103, v113
	v_mov_b32_e32 v104, v113
	v_lshlrev_b32_e32 v100, 3, v120
	v_mov_b32_e32 v97, v96
	v_cndmask_b32_e32 v48, 0, v105, vcc
	v_mov_b32_dpp v49, v105 row_shl:4 row_mask:0xf bank_mask:0x1 bound_ctrl:1
	v_mov_b32_dpp v50, v105 row_shl:8 row_mask:0xf bank_mask:0x1 bound_ctrl:1
	v_mov_b32_dpp v51, v105 row_shl:12 row_mask:0xf bank_mask:0x1 bound_ctrl:1
	v_cndmask_b32_e32 v101, 0, v106, vcc
	v_mov_b32_dpp v102, v106 row_shl:4 row_mask:0xf bank_mask:0x1 bound_ctrl:1
	v_mov_b32_dpp v103, v106 row_shl:8 row_mask:0xf bank_mask:0x1 bound_ctrl:1
	v_mov_b32_dpp v104, v106 row_shl:12 row_mask:0xf bank_mask:0x1 bound_ctrl:1
	v_mul_u32_u24_e32 v98, 0xa0, v98
	v_and_b32_e32 v100, 24, v100
	v_mul_u32_u24_e32 v99, 0xa0, v122
	v_permlane32_swap_b32_e32 v96, v97
	v_cvt_pk_bf16_f32 v48, v48, v49
	v_cvt_pk_bf16_f32 v49, v50, v51
	v_cvt_pk_bf16_f32 v50, v101, v102
	v_cvt_pk_bf16_f32 v51, v103, v104
	v_add3_u32 v110, s47, v98, v100
	v_add_u32_e32 v111, v121, v99
	s_waitcnt vmcnt(15)
	ds_write_b128 v111, v[32:35] offset:1024
	s_waitcnt vmcnt(14)
	ds_write_b128 v111, v[36:39] offset:2304
	s_waitcnt vmcnt(13)
	ds_write_b128 v111, v[40:43] offset:3584
	s_waitcnt vmcnt(12)
	ds_write_b128 v111, v[44:47] offset:4864
	ds_read_b64_tr_b16 v[34:35], v110 offset:3584
	ds_read_b64_tr_b16 v[32:33], v110 offset:1024
	ds_read_b64_tr_b16 v[36:37], v110 offset:1056
	ds_read_b64_tr_b16 v[40:41], v110 offset:1088
	ds_read_b64_tr_b16 v[44:45], v110 offset:1120
	ds_read_b64_tr_b16 v[38:39], v110 offset:3616
	ds_read_b64_tr_b16 v[42:43], v110 offset:3648
	ds_read_b64_tr_b16 v[46:47], v110 offset:3680
	ds_read2_b32 v[98:99], v119 offset0:128 offset1:136
	ds_read2_b32 v[106:107], v119 offset0:144 offset1:152
	s_waitcnt lgkmcnt(8)
	v_mfma_f32_16x16x32_bf16 v[32:35], v[76:79], v[32:35], 0
	s_waitcnt lgkmcnt(1)
	v_lshlrev_b32_e32 v98, 9, v98
	v_and_or_b32 v108, v98, s43, v118
	v_lshlrev_b32_e32 v98, 9, v99
	s_waitcnt lgkmcnt(0)
	v_lshlrev_b32_e32 v106, 9, v106
	v_and_or_b32 v109, v98, s43, v118
	v_and_or_b32 v112, v106, s43, v118
	v_lshlrev_b32_e32 v106, 9, v107
	global_load_dwordx4 v[98:101], v108, s[18:19]
	global_load_dwordx4 v[102:105], v109, s[18:19]
	v_and_or_b32 v124, v106, s43, v118
	global_load_dwordx4 v[106:109], v112, s[18:19]
	global_load_dwordx4 v[120:123], v124, s[18:19]
	v_mfma_f32_16x16x32_bf16 v[36:39], v[76:79], v[36:39], 0
	v_mfma_f32_16x16x32_bf16 v[40:43], v[76:79], v[40:43], 0
	v_mfma_f32_16x16x32_bf16 v[44:47], v[76:79], v[44:47], 0
	s_waitcnt vmcnt(15)
	ds_write_b128 v111, v[16:19] offset:1024
	s_waitcnt vmcnt(14)
	ds_write_b128 v111, v[20:23] offset:2304
	s_waitcnt vmcnt(13)
	ds_write_b128 v111, v[24:27] offset:3584
	s_waitcnt vmcnt(12)
	ds_write_b128 v111, v[28:31] offset:4864
	ds_read_b64_tr_b16 v[18:19], v110 offset:3584
	ds_read_b64_tr_b16 v[16:17], v110 offset:1024
	ds_read_b64_tr_b16 v[20:21], v110 offset:1056
	ds_read_b64_tr_b16 v[24:25], v110 offset:1088
	ds_read_b64_tr_b16 v[28:29], v110 offset:1120
	ds_read_b64_tr_b16 v[22:23], v110 offset:3616
	ds_read_b64_tr_b16 v[26:27], v110 offset:3648
	ds_read_b64_tr_b16 v[30:31], v110 offset:3680
	s_waitcnt lgkmcnt(6)
	v_mfma_f32_16x16x32_bf16 v[16:19], v[64:67], v[16:19], v[32:35]
	s_waitcnt lgkmcnt(1)
	v_mfma_f32_16x16x32_bf16 v[24:27], v[64:67], v[24:27], v[40:43]
	s_nop 0
	ds_read2_b32 v[32:33], v119 offset0:160 offset1:168
	s_waitcnt lgkmcnt(0)
	v_lshlrev_b32_e32 v32, 9, v32
	ds_read2_b32 v[40:41], v119 offset0:176 offset1:184
	v_lshlrev_b32_e32 v33, 9, v33
	v_mfma_f32_16x16x32_bf16 v[20:23], v[64:67], v[20:23], v[36:39]
	v_and_or_b32 v32, v32, s43, v118
	s_waitcnt lgkmcnt(0)
	v_lshlrev_b32_e32 v40, 9, v40
	v_and_or_b32 v36, v33, s43, v118
	v_and_or_b32 v112, v40, s43, v118
	v_lshlrev_b32_e32 v40, 9, v41
	global_load_dwordx4 v[32:35], v32, s[18:19]
	s_nop 0
	global_load_dwordx4 v[36:39], v36, s[18:19]
	v_and_or_b32 v124, v40, s43, v118
	global_load_dwordx4 v[40:43], v112, s[18:19]
	global_load_dwordx4 v[76:79], v124, s[18:19]
	v_mfma_f32_16x16x32_bf16 v[28:31], v[64:67], v[28:31], v[44:47]
	s_waitcnt vmcnt(15)
	ds_write_b128 v111, v[0:3] offset:1024
	s_waitcnt vmcnt(14)
	ds_write_b128 v111, v[4:7] offset:2304
	s_waitcnt vmcnt(13)
	ds_write_b128 v111, v[8:11] offset:3584
	s_waitcnt vmcnt(12)
	ds_write_b128 v111, v[12:15] offset:4864
	ds_read_b64_tr_b16 v[2:3], v110 offset:3584
	ds_read_b64_tr_b16 v[0:1], v110 offset:1024
	ds_read_b64_tr_b16 v[4:5], v110 offset:1056
	ds_read_b64_tr_b16 v[8:9], v110 offset:1088
	ds_read_b64_tr_b16 v[12:13], v110 offset:1120
	ds_read_b64_tr_b16 v[6:7], v110 offset:3616
	ds_read_b64_tr_b16 v[10:11], v110 offset:3648
	ds_read_b64_tr_b16 v[14:15], v110 offset:3680
	s_waitcnt lgkmcnt(6)
	v_mfma_f32_16x16x32_bf16 v[0:3], v[52:55], v[0:3], v[16:19]
	s_waitcnt lgkmcnt(1)
	v_mfma_f32_16x16x32_bf16 v[8:11], v[52:55], v[8:11], v[24:27]
	s_nop 0
	ds_read2_b32 v[16:17], v119 offset0:192 offset1:200
	s_waitcnt lgkmcnt(0)
	v_lshlrev_b32_e32 v16, 9, v16
	ds_read2_b32 v[24:25], v119 offset0:208 offset1:216
	v_lshlrev_b32_e32 v17, 9, v17
	v_mfma_f32_16x16x32_bf16 v[4:7], v[52:55], v[4:7], v[20:23]
	v_and_or_b32 v16, v16, s43, v118
	s_waitcnt lgkmcnt(0)
	v_lshlrev_b32_e32 v24, 9, v24
	v_and_or_b32 v20, v17, s43, v118
	v_and_or_b32 v64, v24, s43, v118
	v_lshlrev_b32_e32 v24, 9, v25
	global_load_dwordx4 v[16:19], v16, s[18:19]
	s_nop 0
	global_load_dwordx4 v[20:23], v20, s[18:19]
	v_and_or_b32 v65, v24, s43, v118
	global_load_dwordx4 v[24:27], v64, s[18:19]
	global_load_dwordx4 v[44:47], v65, s[18:19]
	v_mfma_f32_16x16x32_bf16 v[12:15], v[52:55], v[12:15], v[28:31]
	s_waitcnt vmcnt(15)
	ds_write_b128 v111, v[80:83] offset:1024
	s_waitcnt vmcnt(14)
	ds_write_b128 v111, v[84:87] offset:2304
	s_waitcnt vmcnt(13)
	ds_write_b128 v111, v[88:91] offset:3584
	s_waitcnt vmcnt(12)
	ds_write_b128 v111, v[92:95] offset:4864
	ds_read_b64_tr_b16 v[30:31], v110 offset:3584
	ds_read_b64_tr_b16 v[28:29], v110 offset:1024
	ds_read_b64_tr_b16 v[52:53], v110 offset:1056
	ds_read_b64_tr_b16 v[64:65], v110 offset:1088
	ds_read_b64_tr_b16 v[80:81], v110 offset:1120
	ds_read_b64_tr_b16 v[54:55], v110 offset:3616
	ds_read_b64_tr_b16 v[66:67], v110 offset:3648
	ds_read_b64_tr_b16 v[82:83], v110 offset:3680
	s_waitcnt lgkmcnt(6)
	v_mfma_f32_16x16x32_bf16 v[0:3], v[72:75], v[28:31], v[0:3]
	ds_read2_b32 v[28:29], v119 offset0:224 offset1:232
	s_waitcnt lgkmcnt(0)
	v_lshlrev_b32_e32 v28, 9, v28
	v_mfma_f32_16x16x32_bf16 v[8:11], v[72:75], v[64:67], v[8:11]
	ds_read2_b32 v[64:65], v119 offset0:240 offset1:248
	v_and_or_b32 v66, v28, s43, v118
	v_lshlrev_b32_e32 v28, 9, v29
	v_and_or_b32 v67, v28, s43, v118
	v_mfma_f32_16x16x32_bf16 v[4:7], v[72:75], v[52:55], v[4:7]
	s_waitcnt lgkmcnt(0)
	v_lshlrev_b32_e32 v64, 9, v64
	v_and_or_b32 v88, v64, s43, v118
	v_lshlrev_b32_e32 v64, 9, v65
	global_load_dwordx4 v[28:31], v66, s[18:19]
	global_load_dwordx4 v[52:55], v67, s[18:19]
	v_and_or_b32 v89, v64, s43, v118
	global_load_dwordx4 v[64:67], v88, s[18:19]
	global_load_dwordx4 v[84:87], v89, s[18:19]
	v_mfma_f32_16x16x32_bf16 v[12:15], v[72:75], v[80:83], v[12:15]
	s_waitcnt vmcnt(15)
	ds_write_b128 v111, v[98:101] offset:1024
	s_waitcnt vmcnt(14)
	ds_write_b128 v111, v[102:105] offset:2304
	s_waitcnt vmcnt(13)
	ds_write_b128 v111, v[106:109] offset:3584
	s_waitcnt vmcnt(12)
	ds_write_b128 v111, v[120:123] offset:4864
	ds_read_b64_tr_b16 v[74:75], v110 offset:3584
	ds_read_b64_tr_b16 v[72:73], v110 offset:1024
	ds_read_b64_tr_b16 v[80:81], v110 offset:1056
	ds_read_b64_tr_b16 v[88:89], v110 offset:1088
	ds_read_b64_tr_b16 v[92:93], v110 offset:1120
	ds_read_b64_tr_b16 v[82:83], v110 offset:3616
	ds_read_b64_tr_b16 v[90:91], v110 offset:3648
	ds_read_b64_tr_b16 v[94:95], v110 offset:3680
	s_waitcnt lgkmcnt(6)
	v_mfma_f32_16x16x32_bf16 v[0:3], v[68:71], v[72:75], v[0:3]
	s_waitcnt lgkmcnt(2)
	v_mfma_f32_16x16x32_bf16 v[4:7], v[68:71], v[80:83], v[4:7]
	s_waitcnt lgkmcnt(1)
	v_mfma_f32_16x16x32_bf16 v[8:11], v[68:71], v[88:91], v[8:11]
	s_waitcnt lgkmcnt(0)
	v_mfma_f32_16x16x32_bf16 v[12:15], v[68:71], v[92:95], v[12:15]
	s_waitcnt vmcnt(11)
	ds_write_b128 v111, v[32:35] offset:1024
	s_waitcnt vmcnt(10)
	ds_write_b128 v111, v[36:39] offset:2304
	s_waitcnt vmcnt(9)
	ds_write_b128 v111, v[40:43] offset:3584
	s_waitcnt vmcnt(8)
	ds_write_b128 v111, v[76:79] offset:4864
	ds_read_b64_tr_b16 v[34:35], v110 offset:3584
	ds_read_b64_tr_b16 v[32:33], v110 offset:1024
	ds_read_b64_tr_b16 v[36:37], v110 offset:1056
	ds_read_b64_tr_b16 v[40:41], v110 offset:1088
	ds_read_b64_tr_b16 v[68:69], v110 offset:1120
	ds_read_b64_tr_b16 v[38:39], v110 offset:3616
	ds_read_b64_tr_b16 v[42:43], v110 offset:3648
	ds_read_b64_tr_b16 v[70:71], v110 offset:3680
	s_waitcnt lgkmcnt(6)
	v_mfma_f32_16x16x32_bf16 v[0:3], v[60:63], v[32:35], v[0:3]
	s_waitcnt lgkmcnt(2)
	v_mfma_f32_16x16x32_bf16 v[4:7], v[60:63], v[36:39], v[4:7]
	s_waitcnt lgkmcnt(1)
	v_mfma_f32_16x16x32_bf16 v[8:11], v[60:63], v[40:43], v[8:11]
	s_waitcnt lgkmcnt(0)
	v_mfma_f32_16x16x32_bf16 v[12:15], v[60:63], v[68:71], v[12:15]
	s_waitcnt vmcnt(7)
	ds_write_b128 v111, v[16:19] offset:1024
	s_waitcnt vmcnt(6)
	ds_write_b128 v111, v[20:23] offset:2304
	s_waitcnt vmcnt(5)
	ds_write_b128 v111, v[24:27] offset:3584
	s_waitcnt vmcnt(4)
	ds_write_b128 v111, v[44:47] offset:4864
	ds_read_b64_tr_b16 v[18:19], v110 offset:3584
	ds_read_b64_tr_b16 v[16:17], v110 offset:1024
	ds_read_b64_tr_b16 v[20:21], v110 offset:1056
	ds_read_b64_tr_b16 v[24:25], v110 offset:1088
	ds_read_b64_tr_b16 v[32:33], v110 offset:1120
	ds_read_b64_tr_b16 v[22:23], v110 offset:3616
	ds_read_b64_tr_b16 v[26:27], v110 offset:3648
	ds_read_b64_tr_b16 v[34:35], v110 offset:3680
	s_waitcnt lgkmcnt(6)
	v_mfma_f32_16x16x32_bf16 v[0:3], v[56:59], v[16:19], v[0:3]
	s_waitcnt lgkmcnt(2)
	v_mfma_f32_16x16x32_bf16 v[4:7], v[56:59], v[20:23], v[4:7]
	s_waitcnt lgkmcnt(1)
	v_mfma_f32_16x16x32_bf16 v[8:11], v[56:59], v[24:27], v[8:11]
	s_waitcnt lgkmcnt(0)
	v_mfma_f32_16x16x32_bf16 v[16:19], v[56:59], v[32:35], v[12:15]
	s_waitcnt vmcnt(3)
	ds_write_b128 v111, v[28:31] offset:1024
	s_waitcnt vmcnt(2)
	ds_write_b128 v111, v[52:55] offset:2304
	s_waitcnt vmcnt(1)
	ds_write_b128 v111, v[64:67] offset:3584
	s_waitcnt vmcnt(0)
	ds_write_b128 v111, v[84:87] offset:4864
	ds_read_b64_tr_b16 v[14:15], v110 offset:3584
	ds_read_b64_tr_b16 v[12:13], v110 offset:1024
	ds_read_b64_tr_b16 v[20:21], v110 offset:1056
	ds_read_b64_tr_b16 v[24:25], v110 offset:1088
	ds_read_b64_tr_b16 v[28:29], v110 offset:1120
	ds_read_b64_tr_b16 v[22:23], v110 offset:3616
	ds_read_b64_tr_b16 v[26:27], v110 offset:3648
	ds_read_b64_tr_b16 v[30:31], v110 offset:3680
	s_waitcnt lgkmcnt(6)
	v_mfma_f32_16x16x32_bf16 v[12:15], v[48:51], v[12:15], v[0:3]
	v_cmp_gt_u32_e32 vcc, 16, v117
	s_waitcnt lgkmcnt(1)
	v_mfma_f32_16x16x32_bf16 v[0:3], v[48:51], v[24:27], v[8:11]
	s_waitcnt lgkmcnt(0)
	v_mfma_f32_16x16x32_bf16 v[8:11], v[48:51], v[28:31], v[16:19]
	s_nop 2
	v_add_f32_e32 v19, v96, v97
	ds_bpermute_b32 v16, v114, v19
	ds_bpermute_b32 v17, v114, v19 offset:4
	ds_bpermute_b32 v18, v114, v19 offset:8
	ds_bpermute_b32 v19, v114, v19 offset:12
	v_mfma_f32_16x16x32_bf16 v[4:7], v[48:51], v[20:23], v[4:7]
	s_and_saveexec_b64 s[8:9], vcc
	s_cbranch_execz .LBB0_1251
	s_waitcnt lgkmcnt(0)
	v_div_scale_f32 v20, s[18:19], v19, v19, 1.0
	v_rcp_f32_e32 v21, v20
	v_div_scale_f32 v22, vcc, 1.0, v19, 1.0
	v_lshlrev_b32_e32 v112, 1, v116
	v_fma_f32 v23, -v20, v21, 1.0
	v_fmac_f32_e32 v21, v23, v21
	v_mul_f32_e32 v23, v22, v21
	v_fma_f32 v24, -v20, v23, v22
	v_fmac_f32_e32 v23, v24, v21
	v_fma_f32 v20, -v20, v23, v22
	v_div_scale_f32 v22, s[18:19], v18, v18, 1.0
	v_rcp_f32_e32 v24, v22
	v_div_fmas_f32 v20, v20, v21, v23
	v_div_fixup_f32 v19, v20, v19, 1.0
	v_fma_f32 v20, -v22, v24, 1.0
	v_fmac_f32_e32 v24, v20, v24
	v_div_scale_f32 v20, vcc, 1.0, v18, 1.0
	v_mul_f32_e32 v21, v20, v24
	v_fma_f32 v23, -v22, v21, v20
	v_fmac_f32_e32 v21, v23, v24
	v_fma_f32 v20, -v22, v21, v20
	v_div_scale_f32 v22, s[18:19], v17, v17, 1.0
	v_rcp_f32_e32 v23, v22
	v_div_fmas_f32 v20, v20, v24, v21
	v_div_fixup_f32 v18, v20, v18, 1.0
	v_fma_f32 v20, -v22, v23, 1.0
	v_fmac_f32_e32 v23, v20, v23
	v_div_scale_f32 v20, vcc, 1.0, v17, 1.0
	v_mul_f32_e32 v21, v20, v23
	v_fma_f32 v24, -v22, v21, v20
	v_fmac_f32_e32 v21, v24, v23
	v_fma_f32 v20, -v22, v21, v20
	v_div_scale_f32 v22, s[18:19], v16, v16, 1.0
	v_rcp_f32_e32 v24, v22
	v_div_fmas_f32 v20, v20, v23, v21
	v_div_fixup_f32 v20, v20, v17, 1.0
	v_fma_f32 v17, -v22, v24, 1.0
	v_fmac_f32_e32 v24, v17, v24
	v_div_scale_f32 v17, vcc, 1.0, v16, 1.0
	v_mul_f32_e32 v21, v17, v24
	v_fma_f32 v23, -v22, v21, v17
	v_fmac_f32_e32 v21, v23, v24
	v_fma_f32 v17, -v22, v21, v17
	v_div_fmas_f32 v17, v17, v24, v21
	v_div_fixup_f32 v21, v17, v16, 1.0
	v_mul_f32_e32 v12, v12, v21
	v_mul_f32_e32 v4, v4, v21
	v_mul_f32_e32 v0, v0, v21
	v_mul_f32_e32 v8, v8, v21
	v_mul_f32_e32 v13, v13, v20
	v_mul_f32_e32 v5, v5, v20
	v_mul_f32_e32 v1, v1, v20
	v_mul_f32_e32 v9, v9, v20
	v_mul_f32_e32 v14, v14, v18
	v_mul_f32_e32 v6, v6, v18
	v_mul_f32_e32 v2, v2, v18
	v_mul_f32_e32 v10, v10, v18
	v_mul_f32_e32 v15, v15, v19
	v_mul_f32_e32 v7, v7, v19
	v_mul_f32_e32 v3, v3, v19
	v_mul_f32_e32 v11, v11, v19
	v_lshl_add_u32 v25, v116, 1, s47
	v_cvt_pk_bf16_f32 v12, v12, v4
	v_cvt_pk_bf16_f32 v0, v0, v8
	v_cvt_pk_bf16_f32 v13, v13, v5
	v_cvt_pk_bf16_f32 v1, v1, v9
	v_cvt_pk_bf16_f32 v14, v14, v6
	v_cvt_pk_bf16_f32 v2, v2, v10
	v_cvt_pk_bf16_f32 v15, v15, v7
	v_cvt_pk_bf16_f32 v3, v3, v11
	ds_write_b16 v25, v12 offset:1024
	ds_write_b16_d16_hi v25, v12 offset:1056
	ds_write_b16 v25, v0 offset:1088
	ds_write_b16_d16_hi v25, v0 offset:1120
	ds_write_b16 v25, v13 offset:1152
	ds_write_b16_d16_hi v25, v13 offset:1184
	ds_write_b16 v25, v1 offset:1216
	ds_write_b16_d16_hi v25, v1 offset:1248
	ds_write_b16 v25, v14 offset:1280
	ds_write_b16_d16_hi v25, v14 offset:1312
	ds_write_b16 v25, v2 offset:1344
	ds_write_b16_d16_hi v25, v2 offset:1376
	ds_write_b16 v25, v15 offset:1408
	ds_write_b16_d16_hi v25, v15 offset:1440
	ds_write_b16 v25, v3 offset:1472
	ds_write_b16_d16_hi v25, v3 offset:1504
	s_mov_b32 exec_lo, -1
	s_mov_b32 exec_hi, 0
	v_lshl_add_u32 v26, v117, 4, s47
	v_lshlrev_b32_e32 v27, 4, v117
	s_add_u32 s18, s16, s14
	s_addc_u32 s19, s17, s15
	ds_read_b128 v[28:31], v26 offset:1024
	s_waitcnt lgkmcnt(0)
	global_store_dwordx4 v27, v[28:31], s[18:19]
	s_branch .LBB0_1251
